# seam 1: group-local ARRIVE (store drain + barrier + atomic) moved into the out-proj prologue after its first 8 stage loads (vmcnt(8) instead of vmcnt(0)); on top of v23
# baseline (speedup 1.0000x reference)
; __device__ __forceinline__ unsigned xb_add(unsigned* p, unsigned v) { return __hip_atomic_fetch_add(p, v, __ATOMIC_RELAXED, __HIP_MEMORY_SCOPE_AGENT); }
; __device__ __forceinline__ bool xb_thread0(int wave) { return wave == 0 && hw_lane() == 0; }
; #define BOTH(k) (IN(k) && IN((k) + 1))
; __global__ void __launch_bounds__(NWAVES * 64, 2) mk_fwd(Args args) {
;     ...
;         if (BOTH(4)) { if (F.G == 256 && lo == 0 && hi == 7 && __hip_atomic_load((unsigned*)(F.ctl + CW_LB + 1024), RLX_AGENT) == 0u) { asm volatile("s_waitcnt vmcnt(0)" ::: "memory"); __syncthreads();
;                 if (xb_thread0(F.wave)) { __builtin_amdgcn_s_waitcnt(0); (void)xb_add((unsigned*)(F.ctl + CW_LB + 2048 + 64 * (F.vcu >> 2)), 1u); } }
.LBB0_769:
	s_mov_b32 s98, 0
	v_readlane_b32 s28, v252, 6
	v_readlane_b32 s29, v252, 7
	v_readlane_b32 s96, v252, 14
	s_cmp_lt_i32 s29, 6
	v_readlane_b32 s97, v252, 15
	v_readlane_b32 s71, v252, 13
	v_readlane_b32 s30, v252, 8
	v_readlane_b32 s31, v252, 9
	s_cbranch_scc1 .LBB0_834
	v_readlane_b32 s0, v252, 2
	s_cmpk_lg_i32 s0, 0x100
	s_cselect_b64 s[0:1], -1, 0
	s_cmp_lg_u32 s28, 0
	s_cselect_b64 s[2:3], -1, 0
	s_or_b64 s[0:1], s[2:3], s[0:1]
	s_cmp_lg_u32 s29, 7
	s_cselect_b64 s[2:3], -1, 0
	s_or_b64 s[2:3], s[0:1], s[2:3]
	s_mov_b64 s[0:1], 0
	s_and_b64 vcc, exec, s[2:3]
	s_cbranch_vccnz .LBB0_773
	v_mov_b32_e32 v0, 0x11000
	global_load_dword v0, v0, s[96:97] sc1
	s_mov_b64 s[0:1], -1
	s_waitcnt vmcnt(0)
	v_mov_b32_e32 v253, v0
	v_cmp_ne_u32_e64 s[2:3], 0, v0
	s_andn2_b64 vcc, exec, s[2:3]
	s_cbranch_vccz .LBB0_774

; __device__ __forceinline__ unsigned xb_add(unsigned* p, unsigned v) { return __hip_atomic_fetch_add(p, v, __ATOMIC_RELAXED, __HIP_MEMORY_SCOPE_AGENT); }
; __device__ __forceinline__ bool xb_thread0(int wave) { return wave == 0 && hw_lane() == 0; }
; #define BOTH(k) (IN(k) && IN((k) + 1))
; __global__ void __launch_bounds__(NWAVES * 64, 2) mk_fwd(Args args) {
;     ...
;         if (BOTH(4)) { if (F.G == 256 && lo == 0 && hi == 7 && __hip_atomic_load((unsigned*)(F.ctl + CW_LB + 1024), RLX_AGENT) == 0u) { asm volatile("s_waitcnt vmcnt(0)" ::: "memory"); __syncthreads();
;                 if (xb_thread0(F.wave)) { __builtin_amdgcn_s_waitcnt(0); (void)xb_add((unsigned*)(F.ctl + CW_LB + 2048 + 64 * (F.vcu >> 2)), 1u); } }
.LBB0_829:
	s_mov_b32 s98, 1

; #define PG8_WAIT_V(n) asm volatile("s_waitcnt vmcnt(" #n ")" ::: "memory")
; #define PG8_BAR __builtin_amdgcn_s_barrier()
; #define BOTH(k) (IN(k) && IN((k) + 1))
; template <int ROT, class Epi0, class Epi1, class Late, class Post0>
; __device__ __forceinline__ void gemm_phase_pair(PG8_LAS unsigned char* lds, const Gemm g0, const Gemm g1, const Unit u, const Epi0& E0, const Epi1& E1, int wid_in, const Late& late, const Post0& post0) {
;     ...
;     for (int i = 0; i < 2; ++i) { int R, C; stage_rc(tid * 16 + i * 8192, R, C); const int Rb0 = Epi0::PERM ? ((R & ~31) + perm32(R & 31)) : R;
;         vA0[i] = (unsigned)(R * K0 + C) * 2u; vB0[i] = (unsigned)(Rb0 * K0 + C) * 2u; }
;     ...
;     const size_t kstep = (size_t)(BK * 2);
;     const size_t hs0 = (size_t)HALF * K0 * 2, hs1 = (size_t)HALF * K1 * 2;
;     const unsigned ldsw = (unsigned)wid * 1024u;
;     const int aoff = lds_byte(wr * 64 + fr, fq * 8), boff = lds_byte(wc * 32 + fr, fq * 8);
;     f32x4 acc[2][2][4][2];
; #pragma unroll
;     for (int a = 0; a < 2; ++a)
; #pragma unroll
;         for (int b = 0; b < 2; ++b)
; #pragma unroll
;             for (int m = 0; m < 4; ++m)
; #pragma unroll
;                 for (int n = 0; n < 2; ++n) acc[a][b][m][n] = (f32x4){0.f, 0.f, 0.f, 0.f};
;     bf16x8 At[4][2], B0[2][2], B1[2][2];
;     const char* cA = (const char*)g0.A + (size_t)u.pm * 2 * hs0; const char* cB = (const char*)g0.Bt + (size_t)u.pn * 2 * hs0;
;     const char* nA = (const char*)g1.A + (size_t)u.pm * 2 * hs1; const char* nB = (const char*)g1.Bt + (size_t)u.pn * 2 * hs1;
;     ...
;     PG8_STAGE(PG8_SB(0, 0), cB + PG8_KT(0), vB0); PG8_STAGE(PG8_SB(0, 1), cB + hs0 + PG8_KT(0), vB0); PG8_STAGE(PG8_SA(0, 0), cA + PG8_KT(0), vA0); PG8_STAGE(PG8_SA(0, 1), cA + hs0 + PG8_KT(0), vA0);
;     if (wr == 1) PG8_BAR;
;     PG8_WAIT_V(2); PG8_BAR;
;     PG8_STAGE(PG8_SB(1, 0), cB + PG8_KT(1), vB0); PG8_STAGE(PG8_SA(1, 0), cA + PG8_KT(1), vA0); PG8_STAGE(PG8_SB(1, 1), cB + hs0 + PG8_KT(1), vB0);
; __global__ void __launch_bounds__(NWAVES * 64, 2) mk_fwd(Args args) {
;     ...
;         if (BOTH(4)) { if (F.G == 256 && lo == 0 && hi == 7 && __hip_atomic_load((unsigned*)(F.ctl + CW_LB + 1024), RLX_AGENT) == 0u) { asm volatile("s_waitcnt vmcnt(0)" ::: "memory"); __syncthreads();
;                 if (xb_thread0(F.wave)) { __builtin_amdgcn_s_waitcnt(0); (void)xb_add((unsigned*)(F.ctl + CW_LB + 2048 + 64 * (F.vcu >> 2)), 1u); } }
.LBB0_844:
	v_mbcnt_lo_u32_b32 v143, -1, 0
	v_mbcnt_hi_u32_b32 v143, -1, v143
	s_mov_b32 s4, 0xfffe0
	v_add_u32_e32 v0, s60, v143
	v_ashrrev_i32_e32 v2, 31, v0
	v_lshrrev_b32_e32 v2, 26, v2
	s_waitcnt lgkmcnt(0)
	v_lshlrev_b32_e32 v1, 4, v0
	v_add_u32_e32 v2, v0, v2
	v_bfe_i32 v0, v0, 27, 1
	v_lshrrev_b32_e32 v0, 22, v0
	v_add_u32_e32 v0, v1, v0
	v_and_b32_e32 v0, 0xfffffc00, v0
	v_sub_u32_e32 v0, v1, v0
	v_lshrrev_b32_e32 v3, 4, v0
	v_bitop3_b32 v0, v3, v0, 32 bitop3:0x6c
	v_ashrrev_i32_e32 v4, 31, v0
	v_ashrrev_i32_e32 v2, 6, v2
	v_lshrrev_b32_e32 v4, 26, v4
	v_lshlrev_b32_e32 v3, 3, v2
	v_add_u32_e32 v4, v0, v4
	v_and_b32_e32 v3, -16, v3
	v_ashrrev_i32_e32 v5, 6, v4
	v_and_b32_e32 v4, 0xc0, v4
	v_add_u32_e32 v3, v5, v3
	v_sub_u32_e32 v0, v0, v4
	v_mov_b32_e32 v4, 1
	v_lshlrev_b32_e32 v2, 5, v2
	v_ashrrev_i16_sdwa v0, v4, sext(v0) dst_sel:DWORD dst_unused:UNUSED_PAD src0_sel:DWORD src1_sel:BYTE_0
	v_lshlrev_b32_e32 v6, 1, v3
	v_lshrrev_b32_e32 v7, 2, v3
	v_and_b32_e32 v5, 3, v5
	v_and_b32_e32 v2, 32, v2
	v_bfe_i32 v0, v0, 0, 16
	v_and_b32_e32 v6, 24, v6
	v_and_b32_e32 v7, 4, v7
	v_and_or_b32 v5, v3, s4, v5
	v_or3_b32 v5, v5, v7, v6
	v_add_lshl_u32 v2, v2, v0, 1
	v_add_u32_e32 v1, 0x2000, v1
	v_lshl_add_u32 v0, v3, 12, v2
	v_lshl_add_u32 v132, v5, 12, v2
	v_ashrrev_i32_e32 v2, 31, v1
	v_lshrrev_b32_e32 v2, 22, v2
	v_add_u32_e32 v2, v1, v2
	v_ashrrev_i32_e32 v2, 10, v2
	v_mul_i32_i24_e32 v3, 0x400, v2
	v_sub_u32_e32 v1, v1, v3
	v_lshrrev_b32_e32 v3, 4, v1
	v_bitop3_b32 v1, v3, v1, 32 bitop3:0x6c
	v_ashrrev_i32_e32 v5, 31, v1
	v_lshrrev_b32_e32 v5, 26, v5
	v_lshlrev_b32_e32 v3, 3, v2
	v_add_u32_e32 v5, v1, v5
	v_and_b32_e32 v3, -16, v3
	v_ashrrev_i32_e32 v6, 6, v5
	v_add_u32_e32 v3, v6, v3
	v_and_b32_e32 v6, 3, v6
	v_and_or_b32 v6, v3, s4, v6
	v_readlane_b32 s4, v252, 5
	s_ashr_i32 s15, s14, 31
	s_ashr_i32 s9, s8, 31
	s_lshr_b32 s6, s71, 8
	v_and_b32_e32 v5, 0xc0, v5
	s_lshl_b32 s36, s4, 10
	s_lshl_b64 s[18:19], s[14:15], 20
	s_lshl_b64 s[20:21], s[8:9], 20
	v_sub_u32_e32 v1, v1, v5
	s_add_u32 s7, s96, s20
	v_lshlrev_b32_e32 v2, 5, v2
	v_ashrrev_i16_sdwa v1, v4, sext(v1) dst_sel:DWORD dst_unused:UNUSED_PAD src0_sel:DWORD src1_sel:BYTE_0
	s_addc_u32 s13, s97, s21
	v_and_b32_e32 v2, 32, v2
	v_bfe_i32 v1, v1, 0, 16
	v_lshlrev_b32_e32 v4, 1, v3
	v_lshrrev_b32_e32 v5, 2, v3
	s_add_u32 s4, s7, 0xd00000
	v_mov_b32_e32 v131, 0
	v_and_b32_e32 v4, 24, v4
	v_and_b32_e32 v5, 4, v5
	v_add_lshl_u32 v1, v2, v1, 1
	s_addc_u32 s5, s13, 0
	v_mov_b32_e32 v133, v131
	v_or3_b32 v4, v6, v5, v4
	v_lshl_add_u32 v128, v3, 12, v1
	s_add_i32 s40, s36, 0
	v_lshl_add_u64 v[2:3], s[4:5], 0, v[132:133]
	s_mov_b64 s[10:11], 0x800
	v_lshl_add_u32 v130, v4, 12, v1
	s_add_i32 m0, s40, 0x10000
	v_lshl_add_u64 v[4:5], v[2:3], 0, s[10:11]
	global_load_lds_dwordx4 v[4:5], off
	v_lshl_add_u64 v[4:5], s[4:5], 0, v[130:131]
	s_add_i32 m0, s40, 0x12000
	v_lshl_add_u64 v[6:7], v[4:5], 0, s[10:11]
	s_add_u32 s12, s7, 0xd80800
	global_load_lds_dwordx4 v[6:7], off
	s_addc_u32 s13, s13, 0
	s_add_i32 m0, s40, 0x14000
	v_mov_b32_e32 v1, v131
	global_load_lds_dwordx4 v132, s[12:13]
	s_add_i32 m0, s40, 0x16000
	s_add_u32 s7, s96, s18
	global_load_lds_dwordx4 v130, s[12:13]
	s_addc_u32 s12, s97, s19
	s_add_u32 s16, s7, 0x8c00000
	s_addc_u32 s17, s12, 0
	v_lshl_add_u64 v[6:7], s[16:17], 0, v[0:1]
	v_lshl_add_u64 v[8:9], v[6:7], 0, s[10:11]
	s_mov_b32 m0, s40
	v_mov_b32_e32 v129, v131
	global_load_lds_dwordx4 v[8:9], off
	v_lshl_add_u64 v[8:9], s[16:17], 0, v[128:129]
	s_add_i32 s45, s40, 0x2000
	v_lshl_add_u64 v[10:11], v[8:9], 0, s[10:11]
	s_add_u32 s10, s7, 0x8c80800
	s_mov_b32 m0, s45
	s_addc_u32 s11, s12, 0
	s_add_i32 s34, s40, 0x4000
	global_load_lds_dwordx4 v[10:11], off
	s_mov_b32 m0, s34
	s_add_i32 s35, s40, 0x6000
	global_load_lds_dwordx4 v0, s[10:11]
	s_mov_b32 m0, s35
	s_cmp_eq_u32 s6, 1
	global_load_lds_dwordx4 v128, s[10:11]
	s_cselect_b64 s[22:23], -1, 0
	s_cmp_eq_u32 s98, 1
	s_cbranch_scc0 .Lseam1_done
	s_waitcnt vmcnt(8)
	s_barrier
	v_readlane_b32 s100, v252, 11
	v_readlane_b32 s101, v252, 12
	s_andn2_b64 vcc, exec, s[100:101]
	s_cbranch_vccnz .Lseam1_done
	v_mbcnt_lo_u32_b32 v240, -1, 0
	v_mbcnt_hi_u32_b32 v240, -1, v240
	v_cmp_eq_u32_e32 vcc, 0, v240
	s_and_saveexec_b64 s[100:101], vcc
	s_cbranch_execz .Lseam1_x
	v_readlane_b32 s99, v252, 4
	s_lshl_b32 s99, s99, 4
	s_andn2_b32 s99, s99, 63
	s_lshl_b32 s99, s99, 2
	v_mov_b32_e32 v241, s99
	v_mov_b32_e32 v240, 1
	v_add_u32_e32 v241, 0x12000, v241
	global_atomic_add v241, v240, s[96:97]
.Lseam1_x:
	s_or_b64 exec, exec, s[100:101]
.Lseam1_done:
	s_cmp_lg_u32 s6, 1
	s_cbranch_scc1 .LBB0_846
	s_barrier
